# s5_gen kt table (C Lambda^k B) on f32 matrix cores (v_mfma_f32_16x16x4_f32, exact f32) replacing packed-VALU p loop
# speedup vs baseline: 1.0166x; 1.0047x over previous
; __device__ __forceinline__ void s5_gen(LAS unsigned char* lds, const S5In P, int g, int q, bf16_t* Bst, bf16_t* Bout, const int tid) {
;     ...
;     { const int di = tid >> 8, k = (tid >> 4) & 15, chb = (tid >> 2) & 3, c2b = tid & 3;
;       float acc[4][4];
; #pragma unroll
;       for (int a_ = 0; a_ < 4; ++a_)
; #pragma unroll
;           for (int b_ = 0; b_ < 4; ++b_) acc[a_][b_] = 0.f;
;       for (int p = 0; p < 64; ++p) { const f32x2v w = pw[(di * 64 + p) * 17 + k]; float zr[4], zi[4];
; #pragma unroll
;           for (int b_ = 0; b_ < 4; ++b_) { const f32x2v b = bb[(di * 64 + p) * 16 + 4 * c2b + b_]; zr[b_] = w.x * b.x - w.y * b.y; zi[b_] = w.x * b.y + w.y * b.x; }
; #pragma unroll
;           for (int a_ = 0; a_ < 4; ++a_) { const f32x2v C = cc[(di * 16 + 4 * chb + a_) * 64 + p];
; #pragma unroll
;               for (int b_ = 0; b_ < 4; ++b_) acc[a_][b_] += C.x * zr[b_] - C.y * zi[b_]; } }
; #pragma unroll
;       for (int a_ = 0; a_ < 4; ++a_)
; #pragma unroll
;           for (int b_ = 0; b_ < 4; ++b_) kt[((di * 16 + k) * 16 + 4 * chb + a_) * 16 + 4 * c2b + b_] = acc[a_][b_]; }
.LBB0_197:
	s_or_b64 exec, exec, s[28:29]
	v_mov_b32_e32 v0, 0
	s_mov_b32 s17, 0
	v_mov_b32_e32 v43, v38
	v_mov_b32_e32 v44, v37
	v_mov_b32_e32 v1, v0
	v_mov_b32_e32 v2, v0
	v_mov_b32_e32 v3, v0
	v_mov_b32_e32 v12, v0
	v_mov_b32_e32 v13, v0
	v_mov_b32_e32 v14, v0
	v_mov_b32_e32 v15, v0
	v_mov_b32_e32 v8, v0
	v_mov_b32_e32 v9, v0
	v_mov_b32_e32 v10, v0
	v_mov_b32_e32 v11, v0
	v_mov_b32_e32 v4, v0
	v_mov_b32_e32 v5, v0
	v_mov_b32_e32 v6, v0
	v_mov_b32_e32 v7, v0
	s_waitcnt lgkmcnt(0)
	s_barrier
	v_mbcnt_lo_u32_b32 v43, -1, 0
	v_mbcnt_hi_u32_b32 v43, -1, v43
	v_and_b32_e32 v44, 15, v43
	v_lshrrev_b32_e32 v45, 4, v43
	v_lshrrev_b32_e32 v32, 6, v66
	s_nop 0
	v_readfirstlane_b32 s42, v32
	s_nop 3
	s_lshr_b32 s43, s42, 2
	s_and_b32 s44, s42, 3
	s_lshl_b32 s44, s44, 2
	s_lshl_b32 s45, s43, 6
	v_add_u32_e32 v32, s45, v45
	v_lshlrev_b32_e32 v200, 7, v32
	v_lshl_add_u32 v200, v44, 3, v200
	v_add_u32_e32 v200, 0x4400, v200
	v_mul_u32_u24_e32 v201, 0x88, v32
	s_lshl_b32 s46, s44, 3
	v_add_u32_e32 v201, s46, v201
	s_lshl_b32 s46, s43, 4
	v_add_u32_e32 v32, s46, v44
	v_lshlrev_b32_e32 v202, 9, v32
	v_lshl_add_u32 v202, v45, 3, v202
	v_add_u32_e32 v202, 0x8400, v202
	s_add_i32 s46, s46, s44
	s_lshl_b32 s46, s46, 10
	v_lshlrev_b32_e32 v203, 8, v45
	v_lshl_add_u32 v203, v44, 2, v203
	v_add_u32_e32 v203, s46, v203
	v_add_u32_e32 v203, 0xc400, v203
	ds_read_b64 v[132:133], v200
	ds_read_b64 v[134:135], v200 offset:512
	ds_read_b64 v[136:137], v200 offset:1024
	ds_read_b64 v[138:139], v200 offset:1536
	ds_read_b64 v[140:141], v200 offset:2048
	ds_read_b64 v[142:143], v200 offset:2560
	ds_read_b64 v[144:145], v200 offset:3072
	ds_read_b64 v[146:147], v200 offset:3584
	ds_read_b64 v[148:149], v200 offset:4096
	ds_read_b64 v[150:151], v200 offset:4608
	ds_read_b64 v[152:153], v200 offset:5120
	ds_read_b64 v[154:155], v200 offset:5632
	ds_read_b64 v[156:157], v200 offset:6144
	ds_read_b64 v[158:159], v200 offset:6656
	ds_read_b64 v[160:161], v200 offset:7168
	ds_read_b64 v[162:163], v200 offset:7680
	ds_read_b64 v[164:165], v202
	ds_read_b64 v[166:167], v202 offset:32
	ds_read_b64 v[168:169], v202 offset:64
	ds_read_b64 v[170:171], v202 offset:96
	ds_read_b64 v[172:173], v202 offset:128
	ds_read_b64 v[174:175], v202 offset:160
	ds_read_b64 v[176:177], v202 offset:192
	ds_read_b64 v[178:179], v202 offset:224
	ds_read_b64 v[180:181], v202 offset:256
	ds_read_b64 v[182:183], v202 offset:288
	ds_read_b64 v[184:185], v202 offset:320
	ds_read_b64 v[186:187], v202 offset:352
	ds_read_b64 v[188:189], v202 offset:384
	ds_read_b64 v[190:191], v202 offset:416
	ds_read_b64 v[192:193], v202 offset:448
	ds_read_b64 v[194:195], v202 offset:480
	ds_read_b64 v[0:1], v201
	ds_read_b64 v[2:3], v201 offset:8
	ds_read_b64 v[4:5], v201 offset:16
	ds_read_b64 v[6:7], v201 offset:24
	ds_read_b64 v[8:9], v201 offset:544
	ds_read_b64 v[10:11], v201 offset:552
	ds_read_b64 v[12:13], v201 offset:560
	ds_read_b64 v[14:15], v201 offset:568
	s_waitcnt lgkmcnt(4)
	v_mul_f32_e32 v16, v165, v1
	v_mul_f32_e32 v17, v165, v0
	v_fma_f32 v16, v164, v0, -v16
	v_fma_f32 v17, -v164, v1, -v17
	v_mul_f32_e32 v18, v165, v3
	v_mul_f32_e32 v19, v165, v2
	v_fma_f32 v18, v164, v2, -v18
	v_fma_f32 v19, -v164, v3, -v19
	v_mul_f32_e32 v20, v165, v5
	v_mul_f32_e32 v21, v165, v4
	v_fma_f32 v20, v164, v4, -v20
	v_fma_f32 v21, -v164, v5, -v21
	v_mul_f32_e32 v22, v165, v7
	v_mul_f32_e32 v23, v165, v6
	v_fma_f32 v22, v164, v6, -v22
	v_fma_f32 v23, -v164, v7, -v23
	s_nop 1
	v_mfma_f32_16x16x4_f32 v[48:51], v16, v132, 0
	v_mfma_f32_16x16x4_f32 v[52:55], v18, v132, 0
	v_mfma_f32_16x16x4_f32 v[56:59], v20, v132, 0
	v_mfma_f32_16x16x4_f32 v[196:199], v22, v132, 0
	v_mfma_f32_16x16x4_f32 v[48:51], v17, v133, v[48:51]
	v_mfma_f32_16x16x4_f32 v[52:55], v19, v133, v[52:55]
	v_mfma_f32_16x16x4_f32 v[56:59], v21, v133, v[56:59]
	v_mfma_f32_16x16x4_f32 v[196:199], v23, v133, v[196:199]
	ds_read_b64 v[0:1], v201 offset:1088
	ds_read_b64 v[2:3], v201 offset:1096
	ds_read_b64 v[4:5], v201 offset:1104
	ds_read_b64 v[6:7], v201 offset:1112
	s_waitcnt lgkmcnt(4)
	v_mul_f32_e32 v16, v167, v9
	v_mul_f32_e32 v17, v167, v8
	v_fma_f32 v16, v166, v8, -v16
	v_fma_f32 v17, -v166, v9, -v17
	v_mul_f32_e32 v18, v167, v11
	v_mul_f32_e32 v19, v167, v10
	v_fma_f32 v18, v166, v10, -v18
	v_fma_f32 v19, -v166, v11, -v19
	v_mul_f32_e32 v20, v167, v13
	v_mul_f32_e32 v21, v167, v12
	v_fma_f32 v20, v166, v12, -v20
	v_fma_f32 v21, -v166, v13, -v21
	v_mul_f32_e32 v22, v167, v15
	v_mul_f32_e32 v23, v167, v14
	v_fma_f32 v22, v166, v14, -v22
	v_fma_f32 v23, -v166, v15, -v23
	s_nop 1
	v_mfma_f32_16x16x4_f32 v[48:51], v16, v134, v[48:51]
	v_mfma_f32_16x16x4_f32 v[52:55], v18, v134, v[52:55]
	v_mfma_f32_16x16x4_f32 v[56:59], v20, v134, v[56:59]
	v_mfma_f32_16x16x4_f32 v[196:199], v22, v134, v[196:199]
	v_mfma_f32_16x16x4_f32 v[48:51], v17, v135, v[48:51]
	v_mfma_f32_16x16x4_f32 v[52:55], v19, v135, v[52:55]
	v_mfma_f32_16x16x4_f32 v[56:59], v21, v135, v[56:59]
	v_mfma_f32_16x16x4_f32 v[196:199], v23, v135, v[196:199]
	ds_read_b64 v[8:9], v201 offset:1632
	ds_read_b64 v[10:11], v201 offset:1640
	ds_read_b64 v[12:13], v201 offset:1648
	ds_read_b64 v[14:15], v201 offset:1656
	s_waitcnt lgkmcnt(4)
; __device__ __forceinline__ void s5_gen(LAS unsigned char* lds, const S5In P, int g, int q, bf16_t* Bst, bf16_t* Bout, const int tid) {
;     ...
;       for (int p = 0; p < 64; ++p) { const f32x2v w = pw[(di * 64 + p) * 17 + k]; float zr[4], zi[4];
; #pragma unroll
;           for (int b_ = 0; b_ < 4; ++b_) { const f32x2v b = bb[(di * 64 + p) * 16 + 4 * c2b + b_]; zr[b_] = w.x * b.x - w.y * b.y; zi[b_] = w.x * b.y + w.y * b.x; }
; #pragma unroll
;           for (int a_ = 0; a_ < 4; ++a_) { const f32x2v C = cc[(di * 16 + 4 * chb + a_) * 64 + p];
; #pragma unroll
;               for (int b_ = 0; b_ < 4; ++b_) acc[a_][b_] += C.x * zr[b_] - C.y * zi[b_]; } }
	v_mul_f32_e32 v16, v169, v1
	v_mul_f32_e32 v17, v169, v0
	v_fma_f32 v16, v168, v0, -v16
	v_fma_f32 v17, -v168, v1, -v17
	v_mul_f32_e32 v18, v169, v3
	v_mul_f32_e32 v19, v169, v2
	v_fma_f32 v18, v168, v2, -v18
	v_fma_f32 v19, -v168, v3, -v19
	v_mul_f32_e32 v20, v169, v5
	v_mul_f32_e32 v21, v169, v4
	v_fma_f32 v20, v168, v4, -v20
	v_fma_f32 v21, -v168, v5, -v21
	v_mul_f32_e32 v22, v169, v7
	v_mul_f32_e32 v23, v169, v6
	v_fma_f32 v22, v168, v6, -v22
	v_fma_f32 v23, -v168, v7, -v23
	s_nop 1
	v_mfma_f32_16x16x4_f32 v[48:51], v16, v136, v[48:51]
	v_mfma_f32_16x16x4_f32 v[52:55], v18, v136, v[52:55]
	v_mfma_f32_16x16x4_f32 v[56:59], v20, v136, v[56:59]
	v_mfma_f32_16x16x4_f32 v[196:199], v22, v136, v[196:199]
	v_mfma_f32_16x16x4_f32 v[48:51], v17, v137, v[48:51]
	v_mfma_f32_16x16x4_f32 v[52:55], v19, v137, v[52:55]
	v_mfma_f32_16x16x4_f32 v[56:59], v21, v137, v[56:59]
	v_mfma_f32_16x16x4_f32 v[196:199], v23, v137, v[196:199]
	ds_read_b64 v[0:1], v201 offset:2176
	ds_read_b64 v[2:3], v201 offset:2184
	ds_read_b64 v[4:5], v201 offset:2192
	ds_read_b64 v[6:7], v201 offset:2200
	s_waitcnt lgkmcnt(4)
	v_mul_f32_e32 v16, v171, v9
	v_mul_f32_e32 v17, v171, v8
	v_fma_f32 v16, v170, v8, -v16
	v_fma_f32 v17, -v170, v9, -v17
	v_mul_f32_e32 v18, v171, v11
	v_mul_f32_e32 v19, v171, v10
	v_fma_f32 v18, v170, v10, -v18
	v_fma_f32 v19, -v170, v11, -v19
	v_mul_f32_e32 v20, v171, v13
	v_mul_f32_e32 v21, v171, v12
	v_fma_f32 v20, v170, v12, -v20
	v_fma_f32 v21, -v170, v13, -v21
	v_mul_f32_e32 v22, v171, v15
	v_mul_f32_e32 v23, v171, v14
	v_fma_f32 v22, v170, v14, -v22
	v_fma_f32 v23, -v170, v15, -v23
	s_nop 1
	v_mfma_f32_16x16x4_f32 v[48:51], v16, v138, v[48:51]
	v_mfma_f32_16x16x4_f32 v[52:55], v18, v138, v[52:55]
	v_mfma_f32_16x16x4_f32 v[56:59], v20, v138, v[56:59]
	v_mfma_f32_16x16x4_f32 v[196:199], v22, v138, v[196:199]
	v_mfma_f32_16x16x4_f32 v[48:51], v17, v139, v[48:51]
	v_mfma_f32_16x16x4_f32 v[52:55], v19, v139, v[52:55]
	v_mfma_f32_16x16x4_f32 v[56:59], v21, v139, v[56:59]
	v_mfma_f32_16x16x4_f32 v[196:199], v23, v139, v[196:199]
	ds_read_b64 v[8:9], v201 offset:2720
	ds_read_b64 v[10:11], v201 offset:2728
	ds_read_b64 v[12:13], v201 offset:2736
	ds_read_b64 v[14:15], v201 offset:2744
	s_waitcnt lgkmcnt(4)
	v_mul_f32_e32 v16, v173, v1
	v_mul_f32_e32 v17, v173, v0
	v_fma_f32 v16, v172, v0, -v16
	v_fma_f32 v17, -v172, v1, -v17
	v_mul_f32_e32 v18, v173, v3
	v_mul_f32_e32 v19, v173, v2
	v_fma_f32 v18, v172, v2, -v18
	v_fma_f32 v19, -v172, v3, -v19
	v_mul_f32_e32 v20, v173, v5
	v_mul_f32_e32 v21, v173, v4
	v_fma_f32 v20, v172, v4, -v20
	v_fma_f32 v21, -v172, v5, -v21
	v_mul_f32_e32 v22, v173, v7
	v_mul_f32_e32 v23, v173, v6
	v_fma_f32 v22, v172, v6, -v22
	v_fma_f32 v23, -v172, v7, -v23
	s_nop 1
	v_mfma_f32_16x16x4_f32 v[48:51], v16, v140, v[48:51]
	v_mfma_f32_16x16x4_f32 v[52:55], v18, v140, v[52:55]
	v_mfma_f32_16x16x4_f32 v[56:59], v20, v140, v[56:59]
	v_mfma_f32_16x16x4_f32 v[196:199], v22, v140, v[196:199]
	v_mfma_f32_16x16x4_f32 v[48:51], v17, v141, v[48:51]
	v_mfma_f32_16x16x4_f32 v[52:55], v19, v141, v[52:55]
	v_mfma_f32_16x16x4_f32 v[56:59], v21, v141, v[56:59]
	v_mfma_f32_16x16x4_f32 v[196:199], v23, v141, v[196:199]
	ds_read_b64 v[0:1], v201 offset:3264
	ds_read_b64 v[2:3], v201 offset:3272
	ds_read_b64 v[4:5], v201 offset:3280
	ds_read_b64 v[6:7], v201 offset:3288
	s_waitcnt lgkmcnt(4)
	v_mul_f32_e32 v16, v175, v9
	v_mul_f32_e32 v17, v175, v8
	v_fma_f32 v16, v174, v8, -v16
	v_fma_f32 v17, -v174, v9, -v17
	v_mul_f32_e32 v18, v175, v11
	v_mul_f32_e32 v19, v175, v10
	v_fma_f32 v18, v174, v10, -v18
	v_fma_f32 v19, -v174, v11, -v19
	v_mul_f32_e32 v20, v175, v13
	v_mul_f32_e32 v21, v175, v12
	v_fma_f32 v20, v174, v12, -v20
	v_fma_f32 v21, -v174, v13, -v21
	v_mul_f32_e32 v22, v175, v15
	v_mul_f32_e32 v23, v175, v14
	v_fma_f32 v22, v174, v14, -v22
	v_fma_f32 v23, -v174, v15, -v23
	s_nop 1
	v_mfma_f32_16x16x4_f32 v[48:51], v16, v142, v[48:51]
	v_mfma_f32_16x16x4_f32 v[52:55], v18, v142, v[52:55]
	v_mfma_f32_16x16x4_f32 v[56:59], v20, v142, v[56:59]
	v_mfma_f32_16x16x4_f32 v[196:199], v22, v142, v[196:199]
	v_mfma_f32_16x16x4_f32 v[48:51], v17, v143, v[48:51]
	v_mfma_f32_16x16x4_f32 v[52:55], v19, v143, v[52:55]
	v_mfma_f32_16x16x4_f32 v[56:59], v21, v143, v[56:59]
	v_mfma_f32_16x16x4_f32 v[196:199], v23, v143, v[196:199]
	ds_read_b64 v[8:9], v201 offset:3808
	ds_read_b64 v[10:11], v201 offset:3816
	ds_read_b64 v[12:13], v201 offset:3824
	ds_read_b64 v[14:15], v201 offset:3832
	s_waitcnt lgkmcnt(4)
	v_mul_f32_e32 v16, v177, v1
	v_mul_f32_e32 v17, v177, v0
	v_fma_f32 v16, v176, v0, -v16
	v_fma_f32 v17, -v176, v1, -v17
	v_mul_f32_e32 v18, v177, v3
	v_mul_f32_e32 v19, v177, v2
	v_fma_f32 v18, v176, v2, -v18
	v_fma_f32 v19, -v176, v3, -v19
	v_mul_f32_e32 v20, v177, v5
	v_mul_f32_e32 v21, v177, v4
	v_fma_f32 v20, v176, v4, -v20
	v_fma_f32 v21, -v176, v5, -v21
	v_mul_f32_e32 v22, v177, v7
	v_mul_f32_e32 v23, v177, v6
	v_fma_f32 v22, v176, v6, -v22
	v_fma_f32 v23, -v176, v7, -v23
	s_nop 1
	v_mfma_f32_16x16x4_f32 v[48:51], v16, v144, v[48:51]
	v_mfma_f32_16x16x4_f32 v[52:55], v18, v144, v[52:55]
	v_mfma_f32_16x16x4_f32 v[56:59], v20, v144, v[56:59]
	v_mfma_f32_16x16x4_f32 v[196:199], v22, v144, v[196:199]
	v_mfma_f32_16x16x4_f32 v[48:51], v17, v145, v[48:51]
	v_mfma_f32_16x16x4_f32 v[52:55], v19, v145, v[52:55]
	v_mfma_f32_16x16x4_f32 v[56:59], v21, v145, v[56:59]
	v_mfma_f32_16x16x4_f32 v[196:199], v23, v145, v[196:199]
	ds_read_b64 v[0:1], v201 offset:4352
	ds_read_b64 v[2:3], v201 offset:4360
	ds_read_b64 v[4:5], v201 offset:4368
	ds_read_b64 v[6:7], v201 offset:4376
	s_waitcnt lgkmcnt(4)
; __device__ __forceinline__ void s5_gen(LAS unsigned char* lds, const S5In P, int g, int q, bf16_t* Bst, bf16_t* Bout, const int tid) {
;     ...
;       for (int p = 0; p < 64; ++p) { const f32x2v w = pw[(di * 64 + p) * 17 + k]; float zr[4], zi[4];
; #pragma unroll
;           for (int b_ = 0; b_ < 4; ++b_) { const f32x2v b = bb[(di * 64 + p) * 16 + 4 * c2b + b_]; zr[b_] = w.x * b.x - w.y * b.y; zi[b_] = w.x * b.y + w.y * b.x; }
; #pragma unroll
;           for (int a_ = 0; a_ < 4; ++a_) { const f32x2v C = cc[(di * 16 + 4 * chb + a_) * 64 + p];
; #pragma unroll
;               for (int b_ = 0; b_ < 4; ++b_) acc[a_][b_] += C.x * zr[b_] - C.y * zi[b_]; } }
	v_mul_f32_e32 v16, v179, v9
	v_mul_f32_e32 v17, v179, v8
	v_fma_f32 v16, v178, v8, -v16
	v_fma_f32 v17, -v178, v9, -v17
	v_mul_f32_e32 v18, v179, v11
	v_mul_f32_e32 v19, v179, v10
	v_fma_f32 v18, v178, v10, -v18
	v_fma_f32 v19, -v178, v11, -v19
	v_mul_f32_e32 v20, v179, v13
	v_mul_f32_e32 v21, v179, v12
	v_fma_f32 v20, v178, v12, -v20
	v_fma_f32 v21, -v178, v13, -v21
	v_mul_f32_e32 v22, v179, v15
	v_mul_f32_e32 v23, v179, v14
	v_fma_f32 v22, v178, v14, -v22
	v_fma_f32 v23, -v178, v15, -v23
	s_nop 1
	v_mfma_f32_16x16x4_f32 v[48:51], v16, v146, v[48:51]
	v_mfma_f32_16x16x4_f32 v[52:55], v18, v146, v[52:55]
	v_mfma_f32_16x16x4_f32 v[56:59], v20, v146, v[56:59]
	v_mfma_f32_16x16x4_f32 v[196:199], v22, v146, v[196:199]
	v_mfma_f32_16x16x4_f32 v[48:51], v17, v147, v[48:51]
	v_mfma_f32_16x16x4_f32 v[52:55], v19, v147, v[52:55]
	v_mfma_f32_16x16x4_f32 v[56:59], v21, v147, v[56:59]
	v_mfma_f32_16x16x4_f32 v[196:199], v23, v147, v[196:199]
	ds_read_b64 v[8:9], v201 offset:4896
	ds_read_b64 v[10:11], v201 offset:4904
	ds_read_b64 v[12:13], v201 offset:4912
	ds_read_b64 v[14:15], v201 offset:4920
	s_waitcnt lgkmcnt(4)
	v_mul_f32_e32 v16, v181, v1
	v_mul_f32_e32 v17, v181, v0
	v_fma_f32 v16, v180, v0, -v16
	v_fma_f32 v17, -v180, v1, -v17
	v_mul_f32_e32 v18, v181, v3
	v_mul_f32_e32 v19, v181, v2
	v_fma_f32 v18, v180, v2, -v18
	v_fma_f32 v19, -v180, v3, -v19
	v_mul_f32_e32 v20, v181, v5
	v_mul_f32_e32 v21, v181, v4
	v_fma_f32 v20, v180, v4, -v20
	v_fma_f32 v21, -v180, v5, -v21
	v_mul_f32_e32 v22, v181, v7
	v_mul_f32_e32 v23, v181, v6
	v_fma_f32 v22, v180, v6, -v22
	v_fma_f32 v23, -v180, v7, -v23
	s_nop 1
	v_mfma_f32_16x16x4_f32 v[48:51], v16, v148, v[48:51]
	v_mfma_f32_16x16x4_f32 v[52:55], v18, v148, v[52:55]
	v_mfma_f32_16x16x4_f32 v[56:59], v20, v148, v[56:59]
	v_mfma_f32_16x16x4_f32 v[196:199], v22, v148, v[196:199]
	v_mfma_f32_16x16x4_f32 v[48:51], v17, v149, v[48:51]
	v_mfma_f32_16x16x4_f32 v[52:55], v19, v149, v[52:55]
	v_mfma_f32_16x16x4_f32 v[56:59], v21, v149, v[56:59]
	v_mfma_f32_16x16x4_f32 v[196:199], v23, v149, v[196:199]
	ds_read_b64 v[0:1], v201 offset:5440
	ds_read_b64 v[2:3], v201 offset:5448
	ds_read_b64 v[4:5], v201 offset:5456
	ds_read_b64 v[6:7], v201 offset:5464
	s_waitcnt lgkmcnt(4)
	v_mul_f32_e32 v16, v183, v9
	v_mul_f32_e32 v17, v183, v8
	v_fma_f32 v16, v182, v8, -v16
	v_fma_f32 v17, -v182, v9, -v17
	v_mul_f32_e32 v18, v183, v11
	v_mul_f32_e32 v19, v183, v10
	v_fma_f32 v18, v182, v10, -v18
	v_fma_f32 v19, -v182, v11, -v19
	v_mul_f32_e32 v20, v183, v13
	v_mul_f32_e32 v21, v183, v12
	v_fma_f32 v20, v182, v12, -v20
	v_fma_f32 v21, -v182, v13, -v21
	v_mul_f32_e32 v22, v183, v15
	v_mul_f32_e32 v23, v183, v14
	v_fma_f32 v22, v182, v14, -v22
	v_fma_f32 v23, -v182, v15, -v23
	s_nop 1
	v_mfma_f32_16x16x4_f32 v[48:51], v16, v150, v[48:51]
	v_mfma_f32_16x16x4_f32 v[52:55], v18, v150, v[52:55]
	v_mfma_f32_16x16x4_f32 v[56:59], v20, v150, v[56:59]
	v_mfma_f32_16x16x4_f32 v[196:199], v22, v150, v[196:199]
	v_mfma_f32_16x16x4_f32 v[48:51], v17, v151, v[48:51]
	v_mfma_f32_16x16x4_f32 v[52:55], v19, v151, v[52:55]
	v_mfma_f32_16x16x4_f32 v[56:59], v21, v151, v[56:59]
	v_mfma_f32_16x16x4_f32 v[196:199], v23, v151, v[196:199]
	ds_read_b64 v[8:9], v201 offset:5984
	ds_read_b64 v[10:11], v201 offset:5992
	ds_read_b64 v[12:13], v201 offset:6000
	ds_read_b64 v[14:15], v201 offset:6008
	s_waitcnt lgkmcnt(4)
	v_mul_f32_e32 v16, v185, v1
	v_mul_f32_e32 v17, v185, v0
	v_fma_f32 v16, v184, v0, -v16
	v_fma_f32 v17, -v184, v1, -v17
	v_mul_f32_e32 v18, v185, v3
	v_mul_f32_e32 v19, v185, v2
	v_fma_f32 v18, v184, v2, -v18
	v_fma_f32 v19, -v184, v3, -v19
	v_mul_f32_e32 v20, v185, v5
	v_mul_f32_e32 v21, v185, v4
	v_fma_f32 v20, v184, v4, -v20
	v_fma_f32 v21, -v184, v5, -v21
	v_mul_f32_e32 v22, v185, v7
	v_mul_f32_e32 v23, v185, v6
	v_fma_f32 v22, v184, v6, -v22
	v_fma_f32 v23, -v184, v7, -v23
	s_nop 1
	v_mfma_f32_16x16x4_f32 v[48:51], v16, v152, v[48:51]
	v_mfma_f32_16x16x4_f32 v[52:55], v18, v152, v[52:55]
	v_mfma_f32_16x16x4_f32 v[56:59], v20, v152, v[56:59]
	v_mfma_f32_16x16x4_f32 v[196:199], v22, v152, v[196:199]
	v_mfma_f32_16x16x4_f32 v[48:51], v17, v153, v[48:51]
	v_mfma_f32_16x16x4_f32 v[52:55], v19, v153, v[52:55]
	v_mfma_f32_16x16x4_f32 v[56:59], v21, v153, v[56:59]
	v_mfma_f32_16x16x4_f32 v[196:199], v23, v153, v[196:199]
	ds_read_b64 v[0:1], v201 offset:6528
	ds_read_b64 v[2:3], v201 offset:6536
	ds_read_b64 v[4:5], v201 offset:6544
	ds_read_b64 v[6:7], v201 offset:6552
	s_waitcnt lgkmcnt(4)
	v_mul_f32_e32 v16, v187, v9
	v_mul_f32_e32 v17, v187, v8
	v_fma_f32 v16, v186, v8, -v16
	v_fma_f32 v17, -v186, v9, -v17
	v_mul_f32_e32 v18, v187, v11
	v_mul_f32_e32 v19, v187, v10
	v_fma_f32 v18, v186, v10, -v18
	v_fma_f32 v19, -v186, v11, -v19
	v_mul_f32_e32 v20, v187, v13
	v_mul_f32_e32 v21, v187, v12
	v_fma_f32 v20, v186, v12, -v20
	v_fma_f32 v21, -v186, v13, -v21
	v_mul_f32_e32 v22, v187, v15
	v_mul_f32_e32 v23, v187, v14
	v_fma_f32 v22, v186, v14, -v22
	v_fma_f32 v23, -v186, v15, -v23
	s_nop 1
	v_mfma_f32_16x16x4_f32 v[48:51], v16, v154, v[48:51]
	v_mfma_f32_16x16x4_f32 v[52:55], v18, v154, v[52:55]
	v_mfma_f32_16x16x4_f32 v[56:59], v20, v154, v[56:59]
	v_mfma_f32_16x16x4_f32 v[196:199], v22, v154, v[196:199]
	v_mfma_f32_16x16x4_f32 v[48:51], v17, v155, v[48:51]
	v_mfma_f32_16x16x4_f32 v[52:55], v19, v155, v[52:55]
	v_mfma_f32_16x16x4_f32 v[56:59], v21, v155, v[56:59]
	v_mfma_f32_16x16x4_f32 v[196:199], v23, v155, v[196:199]
	ds_read_b64 v[8:9], v201 offset:7072
	ds_read_b64 v[10:11], v201 offset:7080
	ds_read_b64 v[12:13], v201 offset:7088
	ds_read_b64 v[14:15], v201 offset:7096
	s_waitcnt lgkmcnt(4)
; __device__ __forceinline__ void s5_gen(LAS unsigned char* lds, const S5In P, int g, int q, bf16_t* Bst, bf16_t* Bout, const int tid) {
;     ...
;       for (int p = 0; p < 64; ++p) { const f32x2v w = pw[(di * 64 + p) * 17 + k]; float zr[4], zi[4];
; #pragma unroll
;           for (int b_ = 0; b_ < 4; ++b_) { const f32x2v b = bb[(di * 64 + p) * 16 + 4 * c2b + b_]; zr[b_] = w.x * b.x - w.y * b.y; zi[b_] = w.x * b.y + w.y * b.x; }
; #pragma unroll
;           for (int a_ = 0; a_ < 4; ++a_) { const f32x2v C = cc[(di * 16 + 4 * chb + a_) * 64 + p];
; #pragma unroll
;               for (int b_ = 0; b_ < 4; ++b_) acc[a_][b_] += C.x * zr[b_] - C.y * zi[b_]; } }
; #pragma unroll
;       for (int a_ = 0; a_ < 4; ++a_)
; #pragma unroll
;           for (int b_ = 0; b_ < 4; ++b_) kt[((di * 16 + k) * 16 + 4 * chb + a_) * 16 + 4 * c2b + b_] = acc[a_][b_]; }
;     __syncthreads();
	v_mul_f32_e32 v16, v189, v1
	v_mul_f32_e32 v17, v189, v0
	v_fma_f32 v16, v188, v0, -v16
	v_fma_f32 v17, -v188, v1, -v17
	v_mul_f32_e32 v18, v189, v3
	v_mul_f32_e32 v19, v189, v2
	v_fma_f32 v18, v188, v2, -v18
	v_fma_f32 v19, -v188, v3, -v19
	v_mul_f32_e32 v20, v189, v5
	v_mul_f32_e32 v21, v189, v4
	v_fma_f32 v20, v188, v4, -v20
	v_fma_f32 v21, -v188, v5, -v21
	v_mul_f32_e32 v22, v189, v7
	v_mul_f32_e32 v23, v189, v6
	v_fma_f32 v22, v188, v6, -v22
	v_fma_f32 v23, -v188, v7, -v23
	s_nop 1
	v_mfma_f32_16x16x4_f32 v[48:51], v16, v156, v[48:51]
	v_mfma_f32_16x16x4_f32 v[52:55], v18, v156, v[52:55]
	v_mfma_f32_16x16x4_f32 v[56:59], v20, v156, v[56:59]
	v_mfma_f32_16x16x4_f32 v[196:199], v22, v156, v[196:199]
	v_mfma_f32_16x16x4_f32 v[48:51], v17, v157, v[48:51]
	v_mfma_f32_16x16x4_f32 v[52:55], v19, v157, v[52:55]
	v_mfma_f32_16x16x4_f32 v[56:59], v21, v157, v[56:59]
	v_mfma_f32_16x16x4_f32 v[196:199], v23, v157, v[196:199]
	ds_read_b64 v[0:1], v201 offset:7616
	ds_read_b64 v[2:3], v201 offset:7624
	ds_read_b64 v[4:5], v201 offset:7632
	ds_read_b64 v[6:7], v201 offset:7640
	s_waitcnt lgkmcnt(4)
	v_mul_f32_e32 v16, v191, v9
	v_mul_f32_e32 v17, v191, v8
	v_fma_f32 v16, v190, v8, -v16
	v_fma_f32 v17, -v190, v9, -v17
	v_mul_f32_e32 v18, v191, v11
	v_mul_f32_e32 v19, v191, v10
	v_fma_f32 v18, v190, v10, -v18
	v_fma_f32 v19, -v190, v11, -v19
	v_mul_f32_e32 v20, v191, v13
	v_mul_f32_e32 v21, v191, v12
	v_fma_f32 v20, v190, v12, -v20
	v_fma_f32 v21, -v190, v13, -v21
	v_mul_f32_e32 v22, v191, v15
	v_mul_f32_e32 v23, v191, v14
	v_fma_f32 v22, v190, v14, -v22
	v_fma_f32 v23, -v190, v15, -v23
	s_nop 1
	v_mfma_f32_16x16x4_f32 v[48:51], v16, v158, v[48:51]
	v_mfma_f32_16x16x4_f32 v[52:55], v18, v158, v[52:55]
	v_mfma_f32_16x16x4_f32 v[56:59], v20, v158, v[56:59]
	v_mfma_f32_16x16x4_f32 v[196:199], v22, v158, v[196:199]
	v_mfma_f32_16x16x4_f32 v[48:51], v17, v159, v[48:51]
	v_mfma_f32_16x16x4_f32 v[52:55], v19, v159, v[52:55]
	v_mfma_f32_16x16x4_f32 v[56:59], v21, v159, v[56:59]
	v_mfma_f32_16x16x4_f32 v[196:199], v23, v159, v[196:199]
	ds_read_b64 v[8:9], v201 offset:8160
	ds_read_b64 v[10:11], v201 offset:8168
	ds_read_b64 v[12:13], v201 offset:8176
	ds_read_b64 v[14:15], v201 offset:8184
	s_waitcnt lgkmcnt(4)
	v_mul_f32_e32 v16, v193, v1
	v_mul_f32_e32 v17, v193, v0
	v_fma_f32 v16, v192, v0, -v16
	v_fma_f32 v17, -v192, v1, -v17
	v_mul_f32_e32 v18, v193, v3
	v_mul_f32_e32 v19, v193, v2
	v_fma_f32 v18, v192, v2, -v18
	v_fma_f32 v19, -v192, v3, -v19
	v_mul_f32_e32 v20, v193, v5
	v_mul_f32_e32 v21, v193, v4
	v_fma_f32 v20, v192, v4, -v20
	v_fma_f32 v21, -v192, v5, -v21
	v_mul_f32_e32 v22, v193, v7
	v_mul_f32_e32 v23, v193, v6
	v_fma_f32 v22, v192, v6, -v22
	v_fma_f32 v23, -v192, v7, -v23
	s_nop 1
	v_mfma_f32_16x16x4_f32 v[48:51], v16, v160, v[48:51]
	v_mfma_f32_16x16x4_f32 v[52:55], v18, v160, v[52:55]
	v_mfma_f32_16x16x4_f32 v[56:59], v20, v160, v[56:59]
	v_mfma_f32_16x16x4_f32 v[196:199], v22, v160, v[196:199]
	v_mfma_f32_16x16x4_f32 v[48:51], v17, v161, v[48:51]
	v_mfma_f32_16x16x4_f32 v[52:55], v19, v161, v[52:55]
	v_mfma_f32_16x16x4_f32 v[56:59], v21, v161, v[56:59]
	v_mfma_f32_16x16x4_f32 v[196:199], v23, v161, v[196:199]
	s_waitcnt lgkmcnt(0)
	v_mul_f32_e32 v16, v195, v9
	v_mul_f32_e32 v17, v195, v8
	v_fma_f32 v16, v194, v8, -v16
	v_fma_f32 v17, -v194, v9, -v17
	v_mul_f32_e32 v18, v195, v11
	v_mul_f32_e32 v19, v195, v10
	v_fma_f32 v18, v194, v10, -v18
	v_fma_f32 v19, -v194, v11, -v19
	v_mul_f32_e32 v20, v195, v13
	v_mul_f32_e32 v21, v195, v12
	v_fma_f32 v20, v194, v12, -v20
	v_fma_f32 v21, -v194, v13, -v21
	v_mul_f32_e32 v22, v195, v15
	v_mul_f32_e32 v23, v195, v14
	v_fma_f32 v22, v194, v14, -v22
	v_fma_f32 v23, -v194, v15, -v23
	s_nop 1
	v_mfma_f32_16x16x4_f32 v[48:51], v16, v162, v[48:51]
	v_mfma_f32_16x16x4_f32 v[52:55], v18, v162, v[52:55]
	v_mfma_f32_16x16x4_f32 v[56:59], v20, v162, v[56:59]
	v_mfma_f32_16x16x4_f32 v[196:199], v22, v162, v[196:199]
	v_mfma_f32_16x16x4_f32 v[48:51], v17, v163, v[48:51]
	v_mfma_f32_16x16x4_f32 v[52:55], v19, v163, v[52:55]
	v_mfma_f32_16x16x4_f32 v[56:59], v21, v163, v[56:59]
	v_mfma_f32_16x16x4_f32 v[196:199], v23, v163, v[196:199]
	s_nop 15
	s_nop 3
	ds_write_b32 v203, v48
	ds_write_b32 v203, v49 offset:64
	ds_write_b32 v203, v50 offset:128
	ds_write_b32 v203, v51 offset:192
	ds_write_b32 v203, v52 offset:1024
	ds_write_b32 v203, v53 offset:1088
	ds_write_b32 v203, v54 offset:1152
	ds_write_b32 v203, v55 offset:1216
	ds_write_b32 v203, v56 offset:2048
	ds_write_b32 v203, v57 offset:2112
	ds_write_b32 v203, v58 offset:2176
	ds_write_b32 v203, v59 offset:2240
	ds_write_b32 v203, v196 offset:3072
	ds_write_b32 v203, v197 offset:3136
	ds_write_b32 v203, v198 offset:3200
	ds_write_b32 v203, v199 offset:3264
	s_and_b32 s48, s53, 3
	s_waitcnt lgkmcnt(0)
	s_barrier
	s_and_saveexec_b64 s[28:29], s[38:39]
	s_movk_i32 s51, 0x5ff
	s_mov_b32 s54, 0xffff0000
	s_cbranch_execz .LBB0_202
; __device__ __forceinline__ unsigned pk2(float lo, float hi) { return f2bf(lo) | (f2bf(hi) << 16); }
; __device__ __forceinline__ void s5_gen(LAS unsigned char* lds, const S5In P, int g, int q, bf16_t* Bst, bf16_t* Bout, const int tid) {
;     ...
;     { const int di = q >> 1, ri = q & 1;
;       for (int cid = tid; cid < 2048; cid += 512) { const int nl = cid >> 5, k0 = (cid & 31) * 8, r = k0 >> 4, ch0 = k0 & 15;
;         const f32x2v w = pw[(di * 64 + nl) * 17 + (di == 0 ? 15 - r : r)]; float v[8];
; #pragma unroll
;         for (int j = 0; j < 8; ++j) { const f32x2v b = bb[(di * 64 + nl) * 16 + ch0 + j]; const float zr = w.x * b.x - w.y * b.y, zi = w.x * b.y + w.y * b.x; v[j] = (ri == 0 ? zr : zi) * P.gain[g * 16 + ch0 + j]; }
;         u32x4 o; o.x = pk2(v[0], v[1]); o.y = pk2(v[2], v[3]); o.z = pk2(v[4], v[5]); o.w = pk2(v[6], v[7]);
;         *(u32x4*)(Bst + ((size_t)g * 256 + q * 64 + nl) * 256 + k0) = o; } }
	v_mbcnt_lo_u32_b32 v43, -1, 0
	v_mbcnt_hi_u32_b32 v43, -1, v43
	v_and_b32_e32 v44, 31, v43
	v_lshrrev_b32_e32 v45, 5, v66
	v_lshrrev_b32_e32 v46, 1, v44
	v_and_b32_e32 v47, 1, v44
	v_lshlrev_b32_e32 v47, 3, v47
	s_lshl_b32 s30, s16, 4
	v_add_u32_e32 v57, s30, v47
	v_lshlrev_b32_e32 v208, 2, v57
	v_lshl_add_u64 v[58:59], s[96:97], 0, v[208:209]
	global_load_dwordx4 v[6:9], v[58:59], off
	global_load_dwordx4 v[10:13], v[58:59], off offset:16
	s_lshr_b32 s42, s48, 1
	s_and_b32 s43, s48, 1
	s_cmp_eq_u32 s43, 0
	s_cselect_b64 s[46:47], -1, 0
	s_lshl_b32 s44, s42, 6
	v_add_u32_e32 v57, s44, v45
	v_xor_b32_e32 v58, 15, v46
	s_cmp_eq_u32 s42, 0
	s_cselect_b64 vcc, -1, 0
	v_cndmask_b32_e32 v58, v46, v58, vcc
	v_mul_u32_u24_e32 v52, 0x88, v57
	v_lshl_add_u32 v52, v58, 3, v52
	v_lshlrev_b32_e32 v53, 7, v57
	v_lshl_add_u32 v53, v47, 3, v53
	v_add_u32_e32 v53, 0x4400, v53
	s_lshl_b32 s45, s16, 8
	s_lshl_b32 s17, s48, 6
	s_add_i32 s45, s45, s17
	v_add_u32_e32 v57, s45, v45
	v_lshlrev_b32_e32 v57, 9, v57
	v_lshl_add_u32 v208, v44, 4, v57
	v_lshl_add_u64 v[48:49], s[18:19], 0, v[208:209]
	s_mov_b64 s[50:51], 0x2000
	s_waitcnt vmcnt(0)
	ds_read_b64 v[4:5], v52
	ds_read_b128 v[14:17], v53
	ds_read_b128 v[18:21], v53 offset:16
	ds_read_b128 v[22:25], v53 offset:32
	ds_read_b128 v[26:29], v53 offset:48
	s_waitcnt lgkmcnt(0)
	v_mul_f32_e32 v30, v5, v15
	v_mul_f32_e32 v31, v5, v14
	v_fma_f32 v30, v4, v14, -v30
	v_fma_f32 v31, v4, v15, v31
	v_cndmask_b32_e64 v14, v31, v30, s[46:47]
	v_mul_f32_e32 v14, v14, v6
	v_mul_f32_e32 v30, v5, v17
	v_mul_f32_e32 v31, v5, v16
	v_fma_f32 v30, v4, v16, -v30
	v_fma_f32 v31, v4, v17, v31
	v_cndmask_b32_e64 v16, v31, v30, s[46:47]
	v_mul_f32_e32 v16, v16, v7
	v_mul_f32_e32 v30, v5, v19
	v_mul_f32_e32 v31, v5, v18
	v_fma_f32 v30, v4, v18, -v30
	v_fma_f32 v31, v4, v19, v31
	v_cndmask_b32_e64 v18, v31, v30, s[46:47]
	v_mul_f32_e32 v18, v18, v8
	v_mul_f32_e32 v30, v5, v21
	v_mul_f32_e32 v31, v5, v20
	v_fma_f32 v30, v4, v20, -v30
	v_fma_f32 v31, v4, v21, v31
	v_cndmask_b32_e64 v20, v31, v30, s[46:47]
	v_mul_f32_e32 v20, v20, v9
	v_mul_f32_e32 v30, v5, v23
	v_mul_f32_e32 v31, v5, v22
	v_fma_f32 v30, v4, v22, -v30
	v_fma_f32 v31, v4, v23, v31
	v_cndmask_b32_e64 v22, v31, v30, s[46:47]
	v_mul_f32_e32 v22, v22, v10
	v_mul_f32_e32 v30, v5, v25
	v_mul_f32_e32 v31, v5, v24
	v_fma_f32 v30, v4, v24, -v30
	v_fma_f32 v31, v4, v25, v31
	v_cndmask_b32_e64 v24, v31, v30, s[46:47]
	v_mul_f32_e32 v24, v24, v11
	v_mul_f32_e32 v30, v5, v27
	v_mul_f32_e32 v31, v5, v26
	v_fma_f32 v30, v4, v26, -v30
	v_fma_f32 v31, v4, v27, v31
	v_cndmask_b32_e64 v26, v31, v30, s[46:47]
	v_mul_f32_e32 v26, v26, v12
	v_mul_f32_e32 v30, v5, v29
	v_mul_f32_e32 v31, v5, v28
	v_fma_f32 v30, v4, v28, -v30
	v_fma_f32 v31, v4, v29, v31
	v_cndmask_b32_e64 v28, v31, v30, s[46:47]
	v_mul_f32_e32 v28, v28, v13
	v_cvt_pk_bf16_f32 v0, v14, v16
	v_cvt_pk_bf16_f32 v1, v18, v20
	v_cvt_pk_bf16_f32 v2, v22, v24
	v_cvt_pk_bf16_f32 v3, v26, v28
	global_store_dwordx4 v[48:49], v[0:3], off
	s_nop 1
	v_lshl_add_u64 v[48:49], v[48:49], 0, s[50:51]
	ds_read_b64 v[4:5], v52 offset:2176
	ds_read_b128 v[14:17], v53 offset:2048
	ds_read_b128 v[18:21], v53 offset:2064
	ds_read_b128 v[22:25], v53 offset:2080
	ds_read_b128 v[26:29], v53 offset:2096
	s_waitcnt lgkmcnt(0)
	v_mul_f32_e32 v30, v5, v15
	v_mul_f32_e32 v31, v5, v14
	v_fma_f32 v30, v4, v14, -v30
	v_fma_f32 v31, v4, v15, v31
	v_cndmask_b32_e64 v14, v31, v30, s[46:47]
	v_mul_f32_e32 v14, v14, v6
	v_mul_f32_e32 v30, v5, v17
	v_mul_f32_e32 v31, v5, v16
	v_fma_f32 v30, v4, v16, -v30
	v_fma_f32 v31, v4, v17, v31
	v_cndmask_b32_e64 v16, v31, v30, s[46:47]
	v_mul_f32_e32 v16, v16, v7
	v_mul_f32_e32 v30, v5, v19
	v_mul_f32_e32 v31, v5, v18
	v_fma_f32 v30, v4, v18, -v30
	v_fma_f32 v31, v4, v19, v31
	v_cndmask_b32_e64 v18, v31, v30, s[46:47]
	v_mul_f32_e32 v18, v18, v8
	v_mul_f32_e32 v30, v5, v21
	v_mul_f32_e32 v31, v5, v20
	v_fma_f32 v30, v4, v20, -v30
	v_fma_f32 v31, v4, v21, v31
	v_cndmask_b32_e64 v20, v31, v30, s[46:47]
	v_mul_f32_e32 v20, v20, v9
	v_mul_f32_e32 v30, v5, v23
	v_mul_f32_e32 v31, v5, v22
	v_fma_f32 v30, v4, v22, -v30
	v_fma_f32 v31, v4, v23, v31
	v_cndmask_b32_e64 v22, v31, v30, s[46:47]
	v_mul_f32_e32 v22, v22, v10
	v_mul_f32_e32 v30, v5, v25
	v_mul_f32_e32 v31, v5, v24
	v_fma_f32 v30, v4, v24, -v30
	v_fma_f32 v31, v4, v25, v31
	v_cndmask_b32_e64 v24, v31, v30, s[46:47]
	v_mul_f32_e32 v24, v24, v11
	v_mul_f32_e32 v30, v5, v27
	v_mul_f32_e32 v31, v5, v26
	v_fma_f32 v30, v4, v26, -v30
	v_fma_f32 v31, v4, v27, v31
	v_cndmask_b32_e64 v26, v31, v30, s[46:47]
	v_mul_f32_e32 v26, v26, v12
	v_mul_f32_e32 v30, v5, v29
	v_mul_f32_e32 v31, v5, v28
	v_fma_f32 v30, v4, v28, -v30
	v_fma_f32 v31, v4, v29, v31
	v_cndmask_b32_e64 v28, v31, v30, s[46:47]
	v_mul_f32_e32 v28, v28, v13
	v_cvt_pk_bf16_f32 v0, v14, v16
	v_cvt_pk_bf16_f32 v1, v18, v20
	v_cvt_pk_bf16_f32 v2, v22, v24
	v_cvt_pk_bf16_f32 v3, v26, v28
	global_store_dwordx4 v[48:49], v[0:3], off
	s_nop 1
	v_lshl_add_u64 v[48:49], v[48:49], 0, s[50:51]
	ds_read_b64 v[4:5], v52 offset:4352
	ds_read_b128 v[14:17], v53 offset:4096
	ds_read_b128 v[18:21], v53 offset:4112
	ds_read_b128 v[22:25], v53 offset:4128
	ds_read_b128 v[26:29], v53 offset:4144
	s_waitcnt lgkmcnt(0)
; __device__ __forceinline__ unsigned pk2(float lo, float hi) { return f2bf(lo) | (f2bf(hi) << 16); }
; __device__ __forceinline__ void s5_gen(LAS unsigned char* lds, const S5In P, int g, int q, bf16_t* Bst, bf16_t* Bout, const int tid) {
;     ...
;       for (int cid = tid; cid < 2048; cid += 512) { const int nl = cid >> 5, k0 = (cid & 31) * 8, r = k0 >> 4, ch0 = k0 & 15;
;         const f32x2v w = pw[(di * 64 + nl) * 17 + (di == 0 ? 15 - r : r)]; float v[8];
; #pragma unroll
;         for (int j = 0; j < 8; ++j) { const f32x2v b = bb[(di * 64 + nl) * 16 + ch0 + j]; const float zr = w.x * b.x - w.y * b.y, zi = w.x * b.y + w.y * b.x; v[j] = (ri == 0 ? zr : zi) * P.gain[g * 16 + ch0 + j]; }
;         u32x4 o; o.x = pk2(v[0], v[1]); o.y = pk2(v[2], v[3]); o.z = pk2(v[4], v[5]); o.w = pk2(v[6], v[7]);
;         *(u32x4*)(Bst + ((size_t)g * 256 + q * 64 + nl) * 256 + k0) = o; } }
	v_mul_f32_e32 v30, v5, v15
	v_mul_f32_e32 v31, v5, v14
	v_fma_f32 v30, v4, v14, -v30
	v_fma_f32 v31, v4, v15, v31
	v_cndmask_b32_e64 v14, v31, v30, s[46:47]
	v_mul_f32_e32 v14, v14, v6
	v_mul_f32_e32 v30, v5, v17
	v_mul_f32_e32 v31, v5, v16
	v_fma_f32 v30, v4, v16, -v30
	v_fma_f32 v31, v4, v17, v31
	v_cndmask_b32_e64 v16, v31, v30, s[46:47]
	v_mul_f32_e32 v16, v16, v7
	v_mul_f32_e32 v30, v5, v19
	v_mul_f32_e32 v31, v5, v18
	v_fma_f32 v30, v4, v18, -v30
	v_fma_f32 v31, v4, v19, v31
	v_cndmask_b32_e64 v18, v31, v30, s[46:47]
	v_mul_f32_e32 v18, v18, v8
	v_mul_f32_e32 v30, v5, v21
	v_mul_f32_e32 v31, v5, v20
	v_fma_f32 v30, v4, v20, -v30
	v_fma_f32 v31, v4, v21, v31
	v_cndmask_b32_e64 v20, v31, v30, s[46:47]
	v_mul_f32_e32 v20, v20, v9
	v_mul_f32_e32 v30, v5, v23
	v_mul_f32_e32 v31, v5, v22
	v_fma_f32 v30, v4, v22, -v30
	v_fma_f32 v31, v4, v23, v31
	v_cndmask_b32_e64 v22, v31, v30, s[46:47]
	v_mul_f32_e32 v22, v22, v10
	v_mul_f32_e32 v30, v5, v25
	v_mul_f32_e32 v31, v5, v24
	v_fma_f32 v30, v4, v24, -v30
	v_fma_f32 v31, v4, v25, v31
	v_cndmask_b32_e64 v24, v31, v30, s[46:47]
	v_mul_f32_e32 v24, v24, v11
	v_mul_f32_e32 v30, v5, v27
	v_mul_f32_e32 v31, v5, v26
	v_fma_f32 v30, v4, v26, -v30
	v_fma_f32 v31, v4, v27, v31
	v_cndmask_b32_e64 v26, v31, v30, s[46:47]
	v_mul_f32_e32 v26, v26, v12
	v_mul_f32_e32 v30, v5, v29
	v_mul_f32_e32 v31, v5, v28
	v_fma_f32 v30, v4, v28, -v30
	v_fma_f32 v31, v4, v29, v31
	v_cndmask_b32_e64 v28, v31, v30, s[46:47]
	v_mul_f32_e32 v28, v28, v13
	v_cvt_pk_bf16_f32 v0, v14, v16
	v_cvt_pk_bf16_f32 v1, v18, v20
	v_cvt_pk_bf16_f32 v2, v22, v24
	v_cvt_pk_bf16_f32 v3, v26, v28
	global_store_dwordx4 v[48:49], v[0:3], off
	s_nop 1
	v_lshl_add_u64 v[48:49], v[48:49], 0, s[50:51]
	ds_read_b64 v[4:5], v52 offset:6528
	ds_read_b128 v[14:17], v53 offset:6144
	ds_read_b128 v[18:21], v53 offset:6160
	ds_read_b128 v[22:25], v53 offset:6176
	ds_read_b128 v[26:29], v53 offset:6192
	s_waitcnt lgkmcnt(0)
	v_mul_f32_e32 v30, v5, v15
	v_mul_f32_e32 v31, v5, v14
	v_fma_f32 v30, v4, v14, -v30
	v_fma_f32 v31, v4, v15, v31
	v_cndmask_b32_e64 v14, v31, v30, s[46:47]
	v_mul_f32_e32 v14, v14, v6
	v_mul_f32_e32 v30, v5, v17
	v_mul_f32_e32 v31, v5, v16
	v_fma_f32 v30, v4, v16, -v30
	v_fma_f32 v31, v4, v17, v31
	v_cndmask_b32_e64 v16, v31, v30, s[46:47]
	v_mul_f32_e32 v16, v16, v7
	v_mul_f32_e32 v30, v5, v19
	v_mul_f32_e32 v31, v5, v18
	v_fma_f32 v30, v4, v18, -v30
	v_fma_f32 v31, v4, v19, v31
	v_cndmask_b32_e64 v18, v31, v30, s[46:47]
	v_mul_f32_e32 v18, v18, v8
	v_mul_f32_e32 v30, v5, v21
	v_mul_f32_e32 v31, v5, v20
	v_fma_f32 v30, v4, v20, -v30
	v_fma_f32 v31, v4, v21, v31
	v_cndmask_b32_e64 v20, v31, v30, s[46:47]
	v_mul_f32_e32 v20, v20, v9
	v_mul_f32_e32 v30, v5, v23
	v_mul_f32_e32 v31, v5, v22
	v_fma_f32 v30, v4, v22, -v30
	v_fma_f32 v31, v4, v23, v31
	v_cndmask_b32_e64 v22, v31, v30, s[46:47]
	v_mul_f32_e32 v22, v22, v10
	v_mul_f32_e32 v30, v5, v25
	v_mul_f32_e32 v31, v5, v24
	v_fma_f32 v30, v4, v24, -v30
	v_fma_f32 v31, v4, v25, v31
	v_cndmask_b32_e64 v24, v31, v30, s[46:47]
	v_mul_f32_e32 v24, v24, v11
	v_mul_f32_e32 v30, v5, v27
	v_mul_f32_e32 v31, v5, v26
	v_fma_f32 v30, v4, v26, -v30
	v_fma_f32 v31, v4, v27, v31
	v_cndmask_b32_e64 v26, v31, v30, s[46:47]
	v_mul_f32_e32 v26, v26, v12
	v_mul_f32_e32 v30, v5, v29
	v_mul_f32_e32 v31, v5, v28
	v_fma_f32 v30, v4, v28, -v30
	v_fma_f32 v31, v4, v29, v31
	v_cndmask_b32_e64 v28, v31, v30, s[46:47]
	v_mul_f32_e32 v28, v28, v13
	v_cvt_pk_bf16_f32 v0, v14, v16
	v_cvt_pk_bf16_f32 v1, v18, v20
	v_cvt_pk_bf16_f32 v2, v22, v24
	v_cvt_pk_bf16_f32 v3, v26, v28
	global_store_dwordx4 v[48:49], v[0:3], off
	s_nop 1
